# FOXIN LDS tables: table loads issued at phase start, reduced and written to LDS just before the first K-loop (overlaps the prologue DMA latency)
# speedup vs baseline: 1.0027x; 1.0022x over previous
.LBB0_123:
	s_cmp_lt_i32 s30, 2
	s_cselect_b64 s[8:9], -1, 0
	s_add_u32 s2, s28, 0x4a0000
	s_addc_u32 s3, s29, 0
	v_writelane_b32 v254, s2, 14
	s_and_b64 s[0:1], s[8:9], s[0:1]
	s_andn2_b64 vcc, exec, s[0:1]
	v_writelane_b32 v254, s3, 15
	v_writelane_b32 v254, s97, 16
	s_cbranch_vccnz .LBB0_295
	v_mbcnt_lo_u32_b32 v232, -1, 0
	v_mbcnt_hi_u32_b32 v232, -1, v232
	s_lshr_b32 s98, s33, 6
	s_and_b32 s99, s16, 7
	s_lshl_b32 s99, s99, 3
	s_bfe_u32 s100, s16, 0x30003
	s_add_i32 s99, s99, s100
	s_lshl_b32 s99, s99, 8
	s_lshl_b32 s100, s98, 5
	s_add_i32 s99, s99, s100
	v_and_b32_e32 v233, 15, v232
	v_lshrrev_b32_e32 v234, 4, v232
	v_add_u32_e32 v235, s99, v233
	v_lshlrev_b32_e32 v236, 6, v235
	v_lshl_add_u32 v236, v234, 4, v236
	s_add_u32 s100, s28, 0x100000
	s_addc_u32 s101, s29, 0
	global_load_dwordx4 v[240:243], v236, s[100:101]
	global_load_dwordx4 v[244:247], v236, s[100:101] offset:1024
	v_lshlrev_b32_e32 v237, 2, v232
	global_load_dword v248, v237, s[62:63]
	global_load_dword v249, v237, s[64:65]
	v_xor_b32_e32 v238, 16, v232
	v_lshlrev_b32_e32 v238, 2, v238
	v_xor_b32_e32 v239, 32, v232
	v_lshlrev_b32_e32 v239, 2, v239
	v_mbcnt_lo_u32_b32 v26, -1, 0
	v_mbcnt_hi_u32_b32 v26, -1, v26
	s_cmpk_lt_i32 s16, 0x400
	v_add_u32_e32 v0, s33, v26
	s_cselect_b64 s[4:5], -1, 0
	s_cmpk_gt_i32 s16, 0x3ff
	v_readfirstlane_b32 s10, v0
	s_cbranch_scc1 .LBB0_127
	s_ashr_i32 s0, s16, 31
	s_lshr_b32 s0, s0, 29
	s_add_i32 s2, s16, s0
	s_and_b32 s0, s2, -8
	s_sub_i32 s3, s16, s0
	s_cmp_gt_i32 s3, -1
	s_cbranch_scc0 .LBB0_128
	s_lshl_b32 s6, s3, 7
	s_cbranch_execz .LBB0_129
	s_branch .LBB0_130

.LBB0_140:
	s_add_u32 s14, s28, 0x4300000
	s_addc_u32 s15, s29, 0
	s_add_u32 s18, s28, 0x6300000
	s_addc_u32 s19, s29, 0
	s_add_u32 s52, s28, 0x8400000
	s_addc_u32 s53, s29, 0
	s_add_u32 s54, s28, 0xa500000
	s_mov_b64 s[56:57], 0x80
	s_addc_u32 s55, s29, 0
	s_and_b32 s94, s11, 3
	s_add_i32 m0, s68, 0x18000
	v_lshl_add_u64 v[8:9], v[8:9], 0, s[56:57]
	s_lshl_b32 s95, s0, 6
	s_lshl_b32 s6, s0, 13
	s_lshl_b32 s7, s94, 12
	s_waitcnt vmcnt(2)
	s_barrier
	global_load_lds_dwordx4 v[8:9], off
	v_lshl_add_u64 v[2:3], v[2:3], 0, s[56:57]
	s_add_i32 m0, s68, 0x1a000
	s_add_i32 s96, s68, 0x8000
	s_add_i32 s71, s68, 0xa000
	global_load_lds_dwordx4 v[2:3], off
	v_lshl_add_u64 v[0:1], v[0:1], 0, s[56:57]
	s_mov_b32 m0, s96
	s_add_u32 s0, s4, 0x40080
	global_load_lds_dwordx4 v[0:1], off
	v_lshl_add_u64 v[0:1], v[6:7], 0, s[56:57]
	s_mov_b32 m0, s71
	s_addc_u32 s1, s5, 0
	global_load_lds_dwordx4 v[0:1], off
	s_add_i32 m0, s68, 0x1c000
	v_lshl_add_u64 v[0:1], s[0:1], 0, v[146:147]
	global_load_lds_dwordx4 v[0:1], off
	v_lshl_add_u64 v[0:1], s[0:1], 0, v[150:151]
	s_add_i32 m0, s68, 0x1e000
	s_cmpk_lt_u32 s10, 0x100
	global_load_lds_dwordx4 v[0:1], off
	v_bfe_u32 v0, v26, 4, 2
	v_lshlrev_b32_e32 v154, 4, v0
	v_lshlrev_b32_e32 v152, 3, v0
	v_lshl_or_b32 v0, v153, 6, v154
	v_and_b32_e32 v1, 32, v4
	v_bitop3_b32 v2, v0, s6, v1 bitop3:0xde
	v_bitop3_b32 v167, v0, s7, v1 bitop3:0xde
	v_lshlrev_b32_e32 v0, 14, v27
	v_and_b32_e32 v0, 0xffff8000, v0
	v_lshl_add_u32 v0, v28, 11, v0
	v_and_b32_e32 v1, 1, v27
	v_lshl_or_b32 v0, v1, 6, v0
	v_lshl_add_u32 v158, v29, 1, v0
	v_lshlrev_b32_e32 v0, 14, v30
	v_and_b32_e32 v0, 0xffff8000, v0
	v_lshl_add_u32 v0, v31, 11, v0
	v_and_b32_e32 v1, 1, v30
	s_waitcnt vmcnt(6)
	v_lshl_or_b32 v0, v1, 6, v0
	s_cselect_b64 s[58:59], -1, 0
	v_mov_b32_e32 v155, 0
	v_lshl_add_u32 v160, v32, 1, v0
	s_add_i32 s72, 0, 0x10000
	s_add_i32 s73, 0, 0x14000
	v_mbcnt_lo_u32_b32 v0, -1, 0
	s_mov_b32 s76, 0
	s_ashr_i32 s10, s17, 31
	s_ashr_i32 s11, s16, 31
	v_lshl_add_u64 v[156:157], s[74:75], 0, v[154:155]
	v_mov_b32_e32 v159, v155
	v_mov_b32_e32 v161, v155
	v_mov_b64_e32 v[162:163], 0x400
	v_mov_b64_e32 v[164:165], 0x3ff
	v_add_u32_e32 v214, s72, v167
	v_add_u32_e32 v215, s73, v167
	v_add_u32_e32 v216, 0, v2
	v_mbcnt_hi_u32_b32 v217, -1, v0
	v_lshlrev_b32_e32 v218, 2, v152
	s_mov_b32 s60, 0x3a800000
	s_mov_b32 s12, 0x800000
	v_mov_b32_e32 v166, 0x358637bd
	v_mov_b32_e32 v219, 0x3e38aa3b
	s_waitcnt vmcnt(6)
	v_add_f32_e32 v240, v241, v240
	v_add_f32_e32 v241, v242, v243
	v_add_f32_e32 v244, v245, v244
	v_add_f32_e32 v245, v246, v247
	v_add_f32_e32 v242, v244, v245
	v_add_f32_e32 v243, v240, v241
	ds_bpermute_b32 v247, v238, v243
	ds_bpermute_b32 v246, v238, v242
	s_waitcnt lgkmcnt(0)
	v_pk_add_f32 v[250:251], v[242:243], v[246:247]
	ds_bpermute_b32 v253, v239, v251
	ds_bpermute_b32 v252, v239, v250
	s_waitcnt lgkmcnt(0)
	v_pk_add_f32 v[250:251], v[250:251], v[252:253]
	s_lshl_b32 s99, s98, 7
	v_lshl_add_u32 v236, v233, 2, s99
	v_add_u32_e32 v236, 0x22800, v236
	ds_write_b32 v236, v251
	ds_write_b32 v236, v250 offset:64
	v_add_u32_e32 v237, 0x22c00, v237
	ds_write_b32 v237, v248
	ds_write_b32 v237, v249 offset:256
	s_waitcnt lgkmcnt(0)
	s_barrier
	s_branch .LBB0_143
